# attention K/V staging by LDS-DMA (global_load_lds, padded LDS image kept, K ring of 3 with buffer 2 in static LDS); both wave types issue the DMA in their softmax half; counted vmcnt waits
# speedup vs baseline: 1.0136x; 1.0108x over previous
.LBB0_218:
	s_bfe_u32 s4, s36, 0x30004
	v_lshl_add_u32 v0, s4, 9, v222
	v_ashrrev_i32_e32 v1, 31, v0
	v_lshl_add_u64 v[0:1], v[0:1], 2, s[14:15]
	global_load_dword v232, v[0:1], off
	s_lshl_b32 s5, s36, 6
	s_and_b32 s66, s5, 0x2000
	s_lshl_b32 s5, s21, 7
	s_add_i32 s5, s5, s58
	s_ashr_i32 s8, s5, 31
	s_add_u32 s62, s5, s66
	s_addc_u32 s63, s8, 0
	v_mov_b32_e32 v1, s63
	s_lshl_b32 s89, s4, 7
	s_lshl_b32 s4, s4, 8
	s_mov_b32 s5, s67
	s_mov_b32 s65, s67
	v_lshl_add_u64 v[2:3], s[66:67], 0, v[146:147]
	v_lshlrev_b64 v[2:3], 10, v[2:3]
	v_mov_b32_e32 v5, v3
	v_add_u32_e32 v20, 0, v159
	s_cmp_eq_u32 s21, 0


	v_or_b32_e32 v0, s62, v144
	v_lshlrev_b64 v[0:1], 11, v[0:1]
	v_lshl_add_u64 v[0:1], s[46:47], 0, v[0:1]
	v_lshl_add_u64 v[0:1], v[0:1], 0, s[4:5]
	v_lshl_add_u64 v[0:1], v[0:1], 0, s[64:65]
	v_lshl_add_u64 v[0:1], v[0:1], 0, v[208:209]
	global_load_dwordx4 v[112:115], v[0:1], off
	global_load_dwordx4 v[116:119], v[0:1], off offset:32
	global_load_dwordx4 v[120:123], v[0:1], off offset:64
	global_load_dwordx4 v[124:127], v[0:1], off offset:96
	s_lshl_b32 s4, s66, 11
	s_lshl_b32 s5, s89, 1
	s_add_u32 s4, s4, s5
	s_add_u32 s28, s10, s4
	s_addc_u32 s29, s11, 0
	s_add_u32 s68, s12, s4
	s_addc_u32 s69, s13, 0
	s_lshl_b32 s32, s56, 10
	v_lshlrev_b32_e32 v138, 4, v246
	v_mov_b32_e32 v142, 0xf0f0f1
	v_mov_b32_e32 v143, 0xcccccd
	s_movk_i32 s86, 0x110
	s_movk_i32 s87, 0x140
	v_add_u32_e32 v139, s32, v138
	v_mul_hi_u32 v140, v139, v142
	v_mul_lo_u32 v141, v140, s86
	v_sub_u32_e32 v141, v139, v141
	v_cmp_gt_u32_e32 vcc, 0x100, v141
	s_nop 1
	v_cndmask_b32_e32 v141, 0, v141, vcc
	v_lshl_add_u32 v128, v140, 11, v141
	v_mov_b32_e32 v129, 0
	v_lshl_add_u64 v[128:129], s[28:29], 0, v[128:129]
	s_add_i32 s65, s32, 0x2000
	v_add_u32_e32 v139, s65, v138
	v_mul_hi_u32 v140, v139, v142
	v_mul_lo_u32 v141, v140, s86
	v_sub_u32_e32 v141, v139, v141
	v_cmp_gt_u32_e32 vcc, 0x100, v141
	s_nop 1
	v_cndmask_b32_e32 v141, 0, v141, vcc
	v_lshl_add_u32 v130, v140, 11, v141
	v_mov_b32_e32 v131, 0
	v_lshl_add_u64 v[130:131], s[28:29], 0, v[130:131]
	v_add_u32_e32 v139, s32, v138
	v_mul_hi_u32 v140, v139, v143
	v_mul_lo_u32 v141, v140, s87
	v_sub_u32_e32 v141, v139, v141
	v_cmp_gt_u32_e32 vcc, 0x100, v141
	s_nop 1
	v_cndmask_b32_e32 v141, 0, v141, vcc
	v_lshl_add_u32 v132, v140, 11, v141
	v_mov_b32_e32 v133, 0
	v_lshl_add_u64 v[132:133], s[68:69], 0, v[132:133]
	v_add_u32_e32 v139, s65, v138
	v_mul_hi_u32 v140, v139, v143
	v_mul_lo_u32 v141, v140, s87
	v_sub_u32_e32 v141, v139, v141
	v_cmp_gt_u32_e32 vcc, 0x100, v141
	s_nop 1
	v_cndmask_b32_e32 v141, 0, v141, vcc
	v_lshl_add_u32 v134, v140, 11, v141
	v_mov_b32_e32 v135, 0
	v_lshl_add_u64 v[134:135], s[68:69], 0, v[134:135]
	s_add_i32 s65, s32, 0x3c00
	s_cmp_eq_u32 s56, 0
	s_cselect_b32 s65, 0x4000, s65
	s_cselect_b32 s86, s86, s87
	s_mov_b32 s87, 0xcccccd
	s_cselect_b32 s87, 0xf0f0f1, s87
	s_cselect_b32 s4, s28, s68
	s_cselect_b32 s5, s29, s69
	v_add_u32_e32 v139, s65, v138
	v_mul_hi_u32 v140, v139, s87
	v_mul_lo_u32 v141, v140, s86
	v_sub_u32_e32 v141, v139, v141
	v_cmp_gt_u32_e32 vcc, 0x100, v141
	s_nop 1
	v_cndmask_b32_e32 v141, 0, v141, vcc
	v_lshl_add_u32 v136, v140, 11, v141
	v_mov_b32_e32 v137, 0
	v_lshl_add_u64 v[136:137], s[4:5], 0, v[136:137]
	s_mov_b32 s28, 0
	s_mov_b32 s29, 0x8800
	s_add_i32 m0, s28, s32
	s_nop 0
	global_load_lds_dwordx4 v[128:129], off
	s_add_i32 m0, m0, 0x2000
	v_lshl_add_u64 v[128:129], v[128:129], 0, s[78:79]
	global_load_lds_dwordx4 v[130:131], off
	v_lshl_add_u64 v[130:131], v[130:131], 0, s[78:79]
	s_cmp_eq_u32 s56, 0
	s_cbranch_scc0 .Ldk_p0
	s_add_i32 m0, s28, 0x4000
	s_nop 0
	global_load_lds_dwordx4 v[136:137], off
	v_lshl_add_u64 v[136:137], v[136:137], 0, s[78:79]
.Ldk_p0:
	s_add_i32 m0, s29, s32
	s_nop 0
	global_load_lds_dwordx4 v[132:133], off
	s_add_i32 m0, m0, 0x2000
	v_lshl_add_u64 v[132:133], v[132:133], 0, s[78:79]
	global_load_lds_dwordx4 v[134:135], off
	v_lshl_add_u64 v[134:135], v[134:135], 0, s[78:79]
	s_cmp_eq_u32 s56, 0
	s_cbranch_scc1 .Ldv_p0
	s_cmp_gt_u32 s56, 4
	s_cbranch_scc1 .Ldv_p0
	s_add_i32 m0, s29, s32
	s_add_i32 m0, m0, 0x3c00
	s_nop 0
	global_load_lds_dwordx4 v[136:137], off
	v_lshl_add_u64 v[136:137], v[136:137], 0, s[78:79]
.Ldv_p0:
	s_movk_i32 s28, 0x4400
	s_mov_b32 s29, 0xd800
	s_add_i32 m0, s28, s32
	s_nop 0
	global_load_lds_dwordx4 v[128:129], off
	s_add_i32 m0, m0, 0x2000
	v_lshl_add_u64 v[128:129], v[128:129], 0, s[78:79]
	global_load_lds_dwordx4 v[130:131], off
	v_lshl_add_u64 v[130:131], v[130:131], 0, s[78:79]
	s_cmp_eq_u32 s56, 0
	s_cbranch_scc0 .Ldk_p1
	s_add_i32 m0, s28, 0x4000
	s_nop 0
	global_load_lds_dwordx4 v[136:137], off
	v_lshl_add_u64 v[136:137], v[136:137], 0, s[78:79]

.Ldv_p1:
	s_cmp_eq_u32 s21, 0
	s_cbranch_scc1 .Lpro_nk2
	s_mov_b32 s28, 0x20400
	s_add_i32 m0, s28, s32
	s_nop 0
	global_load_lds_dwordx4 v[128:129], off
	s_add_i32 m0, m0, 0x2000
	v_lshl_add_u64 v[128:129], v[128:129], 0, s[78:79]
	global_load_lds_dwordx4 v[130:131], off
	v_lshl_add_u64 v[130:131], v[130:131], 0, s[78:79]
	s_cmp_eq_u32 s56, 0
	s_cbranch_scc0 .Ldk_p2
	s_add_i32 m0, s28, 0x4000
	s_nop 0
	global_load_lds_dwordx4 v[136:137], off
	v_lshl_add_u64 v[136:137], v[136:137], 0, s[78:79]
.Ldk_p2:
.Lpro_nk2:
	s_waitcnt vmcnt(0)
	ds_write_b32 v149, v232
	s_waitcnt lgkmcnt(0)
	s_barrier



.LBB0_227:
	s_lshl_b32 s4, s59, 11
	s_and_b32 s5, s4, 0x1000000
	s_lshl_b32 s4, s36, 4
	s_and_b32 s28, s4, 0x700
	v_lshl_or_b32 v96, v148, 1, s28
	v_or_b32_e32 v96, s5, v96
	v_mov_b32_e32 v97, v209
	s_lshl_b32 s21, s21, 9
	s_mov_b32 s65, 2
	s_add_i32 s66, s8, 2
	s_mov_b32 s4, 1
	v_lshl_add_u64 v[174:175], v[170:171], 0, v[96:97]
	v_subrev_u32_e32 v204, s21, v194
	s_add_i32 s33, s61, s8
	s_mov_b32 s87, 0
	s_movk_i32 s68, 0xff00
	s_waitcnt lgkmcnt(0)
	s_barrier
	s_and_b64 vcc, exec, s[16:17]
	s_cbranch_vccz .Latt_p_qk
	s_cmp_ge_u32 s65, s66
	s_cbranch_scc1 .LBB0_228
	s_mov_b32 s5, 0
	s_mov_b32 s28, 0x12800
	s_add_i32 m0, s5, s32
	s_nop 0
	global_load_lds_dwordx4 v[128:129], off
	s_add_i32 m0, m0, 0x2000
	v_lshl_add_u64 v[128:129], v[128:129], 0, s[78:79]
	global_load_lds_dwordx4 v[130:131], off
	v_lshl_add_u64 v[130:131], v[130:131], 0, s[78:79]
	s_cmp_eq_u32 s56, 0
	s_cbranch_scc0 .Ldk_p3
	s_add_i32 m0, s5, 0x4000
	s_nop 0
	global_load_lds_dwordx4 v[136:137], off
	v_lshl_add_u64 v[136:137], v[136:137], 0, s[78:79]
.Ldk_p3:
	s_add_i32 m0, s28, s32
	s_nop 0
	global_load_lds_dwordx4 v[132:133], off
	s_add_i32 m0, m0, 0x2000
	v_lshl_add_u64 v[132:133], v[132:133], 0, s[78:79]
	global_load_lds_dwordx4 v[134:135], off
	v_lshl_add_u64 v[134:135], v[134:135], 0, s[78:79]
	s_cmp_eq_u32 s56, 0
	s_cbranch_scc1 .Ldv_p3
	s_cmp_gt_u32 s56, 4
	s_cbranch_scc1 .Ldv_p3
	s_add_i32 m0, s28, s32
	s_add_i32 m0, m0, 0x3c00
	s_nop 0
	global_load_lds_dwordx4 v[136:137], off
	v_lshl_add_u64 v[136:137], v[136:137], 0, s[78:79]
.Ldv_p3:
	s_branch .LBB0_228
.Latt_p_qk:
	s_cmp_lt_i32 s9, 1
	s_cbranch_scc1 .LBB0_228
	s_movk_i32 s5, 0x4400
	v_add_u32_e32 v205, s5, v192
	ds_read_b128 v[96:99], v205 offset:8704
	ds_read_b128 v[100:103], v205 offset:8736
	ds_read_b128 v[104:107], v205 offset:8768
	ds_read_b128 v[108:111], v205 offset:8800
	ds_read_b128 v[176:179], v205
	ds_read_b128 v[180:183], v205 offset:32
	ds_read_b128 v[184:187], v205 offset:64
	ds_read_b128 v[188:191], v205 offset:96
	s_waitcnt lgkmcnt(7)
	v_mfma_f32_32x32x16_bf16 v[80:95], v[96:99], v[112:115], v[64:79]
	s_waitcnt lgkmcnt(6)
	v_mfma_f32_32x32x16_bf16 v[80:95], v[100:103], v[116:119], v[80:95]
	s_waitcnt lgkmcnt(5)
	v_mfma_f32_32x32x16_bf16 v[80:95], v[104:107], v[120:123], v[80:95]
	s_waitcnt lgkmcnt(4)
	v_mfma_f32_32x32x16_bf16 v[80:95], v[108:111], v[124:127], v[80:95]
	s_waitcnt lgkmcnt(3)
	v_mfma_f32_32x32x16_bf16 v[96:111], v[176:179], v[112:115], v[64:79]
	s_waitcnt lgkmcnt(2)
	v_mfma_f32_32x32x16_bf16 v[96:111], v[180:183], v[116:119], v[96:111]
	s_waitcnt lgkmcnt(1)
	v_mfma_f32_32x32x16_bf16 v[96:111], v[184:187], v[120:123], v[96:111]
	s_waitcnt lgkmcnt(0)
	v_mfma_f32_32x32x16_bf16 v[96:111], v[188:191], v[124:127], v[96:111]
	s_cmp_gt_i32 s33, 2
	s_cbranch_scc1 .LBB0_228
	s_waitcnt lgkmcnt(0)
	v_add_u32_e32 v205, s68, v204
	v_add_u32_e32 v176, 0x17d00, v205
	v_add_u32_e32 v178, 0x17d80, v205
	ds_read2_b32 v[176:177], v176 offset1:1
	ds_read2_b32 v[178:179], v178 offset1:1
	v_add_u32_e32 v180, 0x17d08, v205
	v_add_u32_e32 v182, 0x17d88, v205
	v_add_u32_e32 v184, 0x17d20, v205
	v_add_u32_e32 v186, 0x17da0, v205
	v_add_u32_e32 v188, 0x17d28, v205
	v_add_u32_e32 v190, 0x17da8, v205
	v_add_u32_e32 v206, 0x17d40, v205
	v_add_u32_e32 v210, 0x17dc0, v205
	v_add_u32_e32 v212, 0x17d48, v205
	v_add_u32_e32 v221, 0x17dc8, v205
	ds_read2_b32 v[180:181], v180 offset1:1
	ds_read2_b32 v[182:183], v182 offset1:1
	ds_read2_b32 v[184:185], v184 offset1:1
	ds_read2_b32 v[186:187], v186 offset1:1
	ds_read2_b32 v[188:189], v188 offset1:1
	ds_read2_b32 v[190:191], v190 offset1:1
	ds_read2_b32 v[206:207], v206 offset1:1
	ds_read2_b32 v[210:211], v210 offset1:1
	ds_read2_b32 v[212:213], v212 offset1:1
	ds_read2_b32 v[224:225], v221 offset1:1
	v_add_u32_e32 v221, 0x17d60, v205
	v_add_u32_e32 v223, 0x17de0, v205
	ds_read2_b32 v[226:227], v221 offset1:1
	ds_read2_b32 v[228:229], v223 offset1:1
	v_add_u32_e32 v221, 0x17d68, v205
	v_add_u32_e32 v205, 0x17de8, v205
	ds_read2_b32 v[230:231], v221 offset1:1
	s_waitcnt lgkmcnt(14)
	v_pk_add_f32 v[96:97], v[96:97], v[176:177]
	ds_read2_b32 v[176:177], v205 offset1:1
	s_waitcnt lgkmcnt(3)
	v_pk_add_f32 v[108:109], v[108:109], v[226:227]
	v_pk_add_f32 v[106:107], v[106:107], v[212:213]
	s_waitcnt lgkmcnt(1)
	v_pk_add_f32 v[110:111], v[110:111], v[230:231]
	v_pk_add_f32 v[104:105], v[104:105], v[206:207]
	v_pk_add_f32 v[102:103], v[102:103], v[188:189]
	v_pk_add_f32 v[100:101], v[100:101], v[184:185]
	v_pk_add_f32 v[98:99], v[98:99], v[180:181]
	s_waitcnt lgkmcnt(0)
	v_pk_add_f32 v[94:95], v[94:95], v[176:177]
	v_pk_add_f32 v[92:93], v[92:93], v[228:229]
	v_pk_add_f32 v[90:91], v[90:91], v[224:225]
	v_pk_add_f32 v[88:89], v[88:89], v[210:211]
	v_pk_add_f32 v[86:87], v[86:87], v[190:191]
	v_pk_add_f32 v[84:85], v[84:85], v[186:187]
	v_pk_add_f32 v[82:83], v[82:83], v[182:183]
	v_pk_add_f32 v[80:81], v[80:81], v[178:179]
	s_nop 0
.LBB0_228:
	s_add_i32 s86, s65, -1
	s_bitcmp0_b32 s86, 0
	s_mov_b32 s69, s4
	s_mov_b32 s28, 0x20400
	s_cmp_eq_u32 s69, 0
	s_cselect_b32 s28, 0x4400, s28
	s_cmp_eq_u32 s69, 2
	s_cselect_b32 s28, 0, s28
	s_mul_i32 s5, s69, 0x4400
	s_cselect_b32 s5, 0x20400, s5
	s_mul_i32 s29, s69, 0x5000
	s_addk_i32 s29, 0x5000
	s_cmp_lg_u32 s69, 2
	s_cselect_b32 s29, s29, 0
	s_and_b64 vcc, exec, s[16:17]
	s_cbranch_vccnz .Latt_a
	s_cmp_ge_u32 s65, s66
	s_cbranch_scc1 .Latt_b_nod
	s_add_i32 s4, s65, 1
	s_cmp_ge_u32 s4, s66
	s_cbranch_scc1 .Latt_b_nok
	s_sub_i32 s4, 0x24800, s5
	s_sub_i32 s4, s4, s28
	s_add_i32 m0, s4, s32
	s_nop 0
	global_load_lds_dwordx4 v[128:129], off
	s_add_i32 m0, m0, 0x2000
	v_lshl_add_u64 v[128:129], v[128:129], 0, s[78:79]
	global_load_lds_dwordx4 v[130:131], off
	v_lshl_add_u64 v[130:131], v[130:131], 0, s[78:79]
	s_cmp_eq_u32 s56, 0
	s_cbranch_scc0 .Ldk_b
	s_add_i32 m0, s4, 0x4000
	s_nop 0
	global_load_lds_dwordx4 v[136:137], off
	v_lshl_add_u64 v[136:137], v[136:137], 0, s[78:79]
.Ldk_b:
.Latt_b_nok:
	s_add_i32 s4, s29, 0x8800
	s_add_i32 m0, s4, s32
	s_nop 0
	global_load_lds_dwordx4 v[132:133], off
	s_add_i32 m0, m0, 0x2000
	v_lshl_add_u64 v[132:133], v[132:133], 0, s[78:79]
	global_load_lds_dwordx4 v[134:135], off
	v_lshl_add_u64 v[134:135], v[134:135], 0, s[78:79]
	s_cmp_eq_u32 s56, 0
	s_cbranch_scc1 .Ldv_b
	s_cmp_gt_u32 s56, 4
	s_cbranch_scc1 .Ldv_b
	s_add_i32 m0, s4, s32
	s_add_i32 m0, m0, 0x3c00
	s_nop 0
	global_load_lds_dwordx4 v[136:137], off
	v_lshl_add_u64 v[136:137], v[136:137], 0, s[78:79]
.Ldv_b:
.Latt_b_nod:
	s_cmp_gt_i32 s86, s9
	s_cbranch_scc1 .Latt_b_bar
	v_max_f32_e32 v176, v80, v80
	v_max_f32_e32 v177, v96, v96
	v_max_f32_e32 v176, v177, v176
	v_max3_f32 v177, v81, v98, v82
	v_max3_f32 v176, v176, v97, v99
	v_max3_f32 v177, v177, v100, v84
	v_max3_f32 v176, v176, v83, v101
	v_max3_f32 v177, v177, v102, v86
	v_max3_f32 v176, v176, v85, v103
	v_max3_f32 v177, v177, v104, v88
	v_max3_f32 v176, v176, v87, v105
	v_max3_f32 v177, v177, v106, v90
	v_max3_f32 v176, v176, v89, v107
	v_max3_f32 v177, v177, v108, v92
	v_max3_f32 v176, v176, v91, v109
	v_max3_f32 v177, v177, v110, v94
	v_max3_f32 v176, v176, v93, v111
	v_max3_f32 v176, v176, v95, v177
	v_mov_b32_e32 v177, v176
	s_nop 1
	v_permlane32_swap_b32_e32 v176, v177
	v_max_f32_e32 v177, v177, v177
	v_max_f32_e32 v176, v176, v176
	v_max_f32_e32 v176, v176, v177
	s_mov_b32 s4, 0x41000000
	v_cmp_lt_f32_e32 vcc, s4, v176
	s_cbranch_vccz .Latt_b_exp
	v_max_f32_e32 v64, v176, v176
	v_max_f32_e32 v66, 0, v64
	v_exp_f32_e64 v176, -v66
	v_add_f32_e32 v173, v173, v66
	v_xor_b32_e32 v64, 0x80000000, v173
	v_pk_add_f32 v[96:97], v[96:97], v[66:67] op_sel_hi:[1,0] neg_lo:[0,1] neg_hi:[0,1]
	v_pk_add_f32 v[80:81], v[80:81], v[66:67] op_sel_hi:[1,0] neg_lo:[0,1] neg_hi:[0,1]
	v_pk_add_f32 v[98:99], v[98:99], v[66:67] op_sel_hi:[1,0] neg_lo:[0,1] neg_hi:[0,1]
	v_pk_add_f32 v[82:83], v[82:83], v[66:67] op_sel_hi:[1,0] neg_lo:[0,1] neg_hi:[0,1]
	v_pk_add_f32 v[100:101], v[100:101], v[66:67] op_sel_hi:[1,0] neg_lo:[0,1] neg_hi:[0,1]
	v_pk_add_f32 v[84:85], v[84:85], v[66:67] op_sel_hi:[1,0] neg_lo:[0,1] neg_hi:[0,1]
	v_pk_add_f32 v[102:103], v[102:103], v[66:67] op_sel_hi:[1,0] neg_lo:[0,1] neg_hi:[0,1]
	v_pk_add_f32 v[86:87], v[86:87], v[66:67] op_sel_hi:[1,0] neg_lo:[0,1] neg_hi:[0,1]
	v_pk_add_f32 v[104:105], v[104:105], v[66:67] op_sel_hi:[1,0] neg_lo:[0,1] neg_hi:[0,1]
	v_pk_add_f32 v[88:89], v[88:89], v[66:67] op_sel_hi:[1,0] neg_lo:[0,1] neg_hi:[0,1]
	v_pk_add_f32 v[106:107], v[106:107], v[66:67] op_sel_hi:[1,0] neg_lo:[0,1] neg_hi:[0,1]
	v_pk_add_f32 v[90:91], v[90:91], v[66:67] op_sel_hi:[1,0] neg_lo:[0,1] neg_hi:[0,1]
	v_pk_add_f32 v[108:109], v[108:109], v[66:67] op_sel_hi:[1,0] neg_lo:[0,1] neg_hi:[0,1]
	v_pk_add_f32 v[92:93], v[92:93], v[66:67] op_sel_hi:[1,0] neg_lo:[0,1] neg_hi:[0,1]
	v_pk_add_f32 v[110:111], v[110:111], v[66:67] op_sel_hi:[1,0] neg_lo:[0,1] neg_hi:[0,1]
	v_pk_add_f32 v[94:95], v[94:95], v[66:67] op_sel_hi:[1,0] neg_lo:[0,1] neg_hi:[0,1]
	v_mov_b32_e32 v65, v64
	v_mov_b32_e32 v66, v64
	v_mov_b32_e32 v67, v64
	v_mov_b32_e32 v68, v64
	v_mov_b32_e32 v69, v64
	v_mov_b32_e32 v70, v64
	v_mov_b32_e32 v71, v64
	v_mov_b32_e32 v72, v64
	v_mov_b32_e32 v73, v64
	v_mov_b32_e32 v74, v64
	v_mov_b32_e32 v75, v64
	v_mov_b32_e32 v76, v64
	v_mov_b32_e32 v77, v64
	v_mov_b32_e32 v78, v64
	v_mov_b32_e32 v79, v64
	v_pk_mul_f32 v[46:47], v[46:47], v[176:177] op_sel_hi:[1,0]
	v_pk_mul_f32 v[44:45], v[44:45], v[176:177] op_sel_hi:[1,0]
	v_pk_mul_f32 v[42:43], v[42:43], v[176:177] op_sel_hi:[1,0]
	v_pk_mul_f32 v[40:41], v[40:41], v[176:177] op_sel_hi:[1,0]
	v_pk_mul_f32 v[38:39], v[38:39], v[176:177] op_sel_hi:[1,0]
	v_pk_mul_f32 v[36:37], v[36:37], v[176:177] op_sel_hi:[1,0]
	v_pk_mul_f32 v[34:35], v[34:35], v[176:177] op_sel_hi:[1,0]
	v_pk_mul_f32 v[32:33], v[32:33], v[176:177] op_sel_hi:[1,0]
	v_pk_mul_f32 v[30:31], v[30:31], v[176:177] op_sel_hi:[1,0]
	v_pk_mul_f32 v[28:29], v[28:29], v[176:177] op_sel_hi:[1,0]
	v_pk_mul_f32 v[26:27], v[26:27], v[176:177] op_sel_hi:[1,0]
	v_pk_mul_f32 v[24:25], v[24:25], v[176:177] op_sel_hi:[1,0]
	v_pk_mul_f32 v[22:23], v[22:23], v[176:177] op_sel_hi:[1,0]
	v_pk_mul_f32 v[20:21], v[20:21], v[176:177] op_sel_hi:[1,0]
	v_pk_mul_f32 v[18:19], v[18:19], v[176:177] op_sel_hi:[1,0]
	v_pk_mul_f32 v[16:17], v[16:17], v[176:177] op_sel_hi:[1,0]
	v_pk_mul_f32 v[14:15], v[14:15], v[176:177] op_sel_hi:[1,0]
	v_pk_mul_f32 v[12:13], v[12:13], v[176:177] op_sel_hi:[1,0]
	v_pk_mul_f32 v[10:11], v[10:11], v[176:177] op_sel_hi:[1,0]
	v_pk_mul_f32 v[8:9], v[8:9], v[176:177] op_sel_hi:[1,0]
	v_pk_mul_f32 v[6:7], v[6:7], v[176:177] op_sel_hi:[1,0]
	v_pk_mul_f32 v[4:5], v[4:5], v[176:177] op_sel_hi:[1,0]
	v_pk_mul_f32 v[2:3], v[2:3], v[176:177] op_sel_hi:[1,0]
	v_pk_mul_f32 v[0:1], v[0:1], v[176:177] op_sel_hi:[1,0]
	v_pk_mul_f32 v[62:63], v[62:63], v[176:177] op_sel_hi:[1,0]
	v_pk_mul_f32 v[60:61], v[60:61], v[176:177] op_sel_hi:[1,0]
	v_pk_mul_f32 v[58:59], v[58:59], v[176:177] op_sel_hi:[1,0]
	v_pk_mul_f32 v[56:57], v[56:57], v[176:177] op_sel_hi:[1,0]
	v_pk_mul_f32 v[54:55], v[54:55], v[176:177] op_sel_hi:[1,0]
	v_pk_mul_f32 v[52:53], v[52:53], v[176:177] op_sel_hi:[1,0]
	v_pk_mul_f32 v[50:51], v[50:51], v[176:177] op_sel_hi:[1,0]
	v_pk_mul_f32 v[48:49], v[48:49], v[176:177] op_sel_hi:[1,0]
	v_mul_f32_e32 v172, v172, v176

.Latt_b_bar:
	s_add_i32 s4, s65, 1
	s_cmp_lt_u32 s4, s66
	s_cbranch_scc0 .Lw0_b
	s_cmp_gt_u32 s56, 4
	s_cbranch_scc1 .Lw4_b
	s_waitcnt vmcnt(5) lgkmcnt(0)
	s_branch .Lwd_b
.Lw4_b:
	s_waitcnt vmcnt(4) lgkmcnt(0)
	s_branch .Lwd_b

.Lwd_b:
	s_barrier
	s_cmp_gt_i32 s86, s9
	s_cbranch_scc1 .LBB0_241
	s_cmp_ge_i32 s86, s9
	s_cbranch_scc1 .Latt_b_pvonly
	s_mul_i32 s4, s69, 0x5000
	v_add_u32_e32 v205, s4, v165
	v_add_u32_e32 v206, s28, v192
	ds_read_b64_tr_b16 v[96:97], v205 offset:34816
	ds_read_b64_tr_b16 v[98:99], v205 offset:37376
	ds_read_b64_tr_b16 v[100:101], v205 offset:39936
	ds_read_b64_tr_b16 v[102:103], v205 offset:42496
	ds_read_b64_tr_b16 v[104:105], v205 offset:45056
	ds_read_b64_tr_b16 v[106:107], v205 offset:47616
	ds_read_b64_tr_b16 v[108:109], v205 offset:50176
	ds_read_b64_tr_b16 v[110:111], v205 offset:52736
	ds_read_b64_tr_b16 v[176:177], v205 offset:34880
	ds_read_b64_tr_b16 v[178:179], v205 offset:37440
	ds_read_b64_tr_b16 v[180:181], v205 offset:40000
	ds_read_b64_tr_b16 v[182:183], v205 offset:42560
	ds_read_b64_tr_b16 v[184:185], v205 offset:45120
	ds_read_b64_tr_b16 v[186:187], v205 offset:47680
	s_setprio 1
	s_waitcnt lgkmcnt(12)
	v_mfma_f32_32x32x16_bf16 v[32:47], v[96:99], v[80:83], v[32:47]
	ds_read_b64_tr_b16 v[96:97], v205 offset:50240
	ds_read_b64_tr_b16 v[98:99], v205 offset:52800
	s_waitcnt lgkmcnt(12)
	v_mfma_f32_32x32x16_bf16 v[32:47], v[100:103], v[84:87], v[32:47]
	ds_read_b64_tr_b16 v[100:101], v205 offset:34944
	ds_read_b64_tr_b16 v[102:103], v205 offset:37504
	s_waitcnt lgkmcnt(12)
	v_mfma_f32_32x32x16_bf16 v[32:47], v[104:107], v[88:91], v[32:47]
	ds_read_b64_tr_b16 v[104:105], v205 offset:40064
	ds_read_b64_tr_b16 v[106:107], v205 offset:42624
	s_waitcnt lgkmcnt(12)
	v_mfma_f32_32x32x16_bf16 v[32:47], v[108:111], v[92:95], v[32:47]
	ds_read_b64_tr_b16 v[108:109], v205 offset:45184
	ds_read_b64_tr_b16 v[110:111], v205 offset:47744
	s_waitcnt lgkmcnt(12)
	v_mfma_f32_32x32x16_bf16 v[16:31], v[176:179], v[80:83], v[16:31]
	ds_read_b64_tr_b16 v[176:177], v205 offset:50304
	ds_read_b64_tr_b16 v[178:179], v205 offset:52864
	s_waitcnt lgkmcnt(12)
	v_mfma_f32_32x32x16_bf16 v[16:31], v[180:183], v[84:87], v[16:31]
	ds_read_b64_tr_b16 v[180:181], v205 offset:35008
	ds_read_b64_tr_b16 v[182:183], v205 offset:37568
	s_waitcnt lgkmcnt(12)
	v_mfma_f32_32x32x16_bf16 v[16:31], v[184:187], v[88:91], v[16:31]
	ds_read_b64_tr_b16 v[184:185], v205 offset:40128
	ds_read_b64_tr_b16 v[186:187], v205 offset:42688
	s_waitcnt lgkmcnt(12)
	v_mfma_f32_32x32x16_bf16 v[16:31], v[96:99], v[92:95], v[16:31]
	ds_read_b64_tr_b16 v[96:97], v205 offset:45248
	ds_read_b64_tr_b16 v[98:99], v205 offset:47808
	s_waitcnt lgkmcnt(12)
	v_mfma_f32_32x32x16_bf16 v[0:15], v[100:103], v[80:83], v[0:15]
	ds_read_b64_tr_b16 v[100:101], v205 offset:50368
	ds_read_b64_tr_b16 v[102:103], v205 offset:52928
	s_waitcnt lgkmcnt(12)
	v_mfma_f32_32x32x16_bf16 v[0:15], v[104:107], v[84:87], v[0:15]
	ds_read_b128 v[210:213], v206 offset:8704
	ds_read_b128 v[104:107], v206 offset:8736
	s_waitcnt lgkmcnt(12)
	v_mfma_f32_32x32x16_bf16 v[0:15], v[108:111], v[88:91], v[0:15]
	ds_read_b128 v[108:111], v206 offset:8768
	ds_read_b128 v[188:191], v206
	s_waitcnt lgkmcnt(12)
	v_mfma_f32_32x32x16_bf16 v[0:15], v[176:179], v[92:95], v[0:15]
	ds_read_b128 v[176:179], v206 offset:8800
	ds_read_b128 v[224:227], v206 offset:32
	s_waitcnt lgkmcnt(12)
	v_mfma_f32_32x32x16_bf16 v[48:63], v[180:183], v[80:83], v[48:63]
	ds_read_b128 v[228:231], v206 offset:64
	ds_read_b128 v[248:251], v206 offset:96
	s_waitcnt lgkmcnt(12)
	v_mfma_f32_32x32x16_bf16 v[48:63], v[184:187], v[84:87], v[48:63]
	s_waitcnt lgkmcnt(10)
	v_mfma_f32_32x32x16_bf16 v[48:63], v[96:99], v[88:91], v[48:63]
	s_waitcnt lgkmcnt(8)
	v_mfma_f32_32x32x16_bf16 v[48:63], v[100:103], v[92:95], v[48:63]
	s_waitcnt lgkmcnt(7)
	v_mfma_f32_32x32x16_bf16 v[80:95], v[210:213], v[112:115], v[64:79]
	s_waitcnt lgkmcnt(6)
	v_mfma_f32_32x32x16_bf16 v[80:95], v[104:107], v[116:119], v[80:95]
	s_waitcnt lgkmcnt(5)
	v_mfma_f32_32x32x16_bf16 v[80:95], v[108:111], v[120:123], v[80:95]
	s_waitcnt lgkmcnt(3)
	v_mfma_f32_32x32x16_bf16 v[80:95], v[176:179], v[124:127], v[80:95]
	s_waitcnt lgkmcnt(4)
	v_mfma_f32_32x32x16_bf16 v[96:111], v[188:191], v[112:115], v[64:79]
	s_waitcnt lgkmcnt(2)
	v_mfma_f32_32x32x16_bf16 v[96:111], v[224:227], v[116:119], v[96:111]
	s_waitcnt lgkmcnt(1)
	v_mfma_f32_32x32x16_bf16 v[96:111], v[228:231], v[120:123], v[96:111]
	s_waitcnt lgkmcnt(0)
	v_mfma_f32_32x32x16_bf16 v[96:111], v[248:251], v[124:127], v[96:111]
	s_setprio 0
	s_cmp_gt_i32 s33, 3
	s_cbranch_scc1 .LBB0_241
	s_waitcnt lgkmcnt(0)
	s_add_i32 s4, s68, 0x100
	v_add_u32_e32 v205, s4, v204
	v_add_u32_e32 v176, 0x17d00, v205
	v_add_u32_e32 v178, 0x17d80, v205
	ds_read2_b32 v[176:177], v176 offset1:1
	ds_read2_b32 v[178:179], v178 offset1:1
	v_add_u32_e32 v180, 0x17d08, v205
	v_add_u32_e32 v182, 0x17d88, v205
	v_add_u32_e32 v184, 0x17d20, v205
	v_add_u32_e32 v186, 0x17da0, v205
	v_add_u32_e32 v188, 0x17d28, v205
	v_add_u32_e32 v190, 0x17da8, v205
	v_add_u32_e32 v206, 0x17d40, v205
	v_add_u32_e32 v210, 0x17dc0, v205
	v_add_u32_e32 v212, 0x17d48, v205
	v_add_u32_e32 v221, 0x17dc8, v205
	ds_read2_b32 v[180:181], v180 offset1:1
	ds_read2_b32 v[182:183], v182 offset1:1
	ds_read2_b32 v[184:185], v184 offset1:1
	ds_read2_b32 v[186:187], v186 offset1:1
	ds_read2_b32 v[188:189], v188 offset1:1
	ds_read2_b32 v[190:191], v190 offset1:1
	ds_read2_b32 v[206:207], v206 offset1:1
	ds_read2_b32 v[210:211], v210 offset1:1
	ds_read2_b32 v[212:213], v212 offset1:1
	ds_read2_b32 v[224:225], v221 offset1:1
	v_add_u32_e32 v221, 0x17d60, v205
	v_add_u32_e32 v223, 0x17de0, v205
	ds_read2_b32 v[226:227], v221 offset1:1
	ds_read2_b32 v[228:229], v223 offset1:1
	v_add_u32_e32 v221, 0x17d68, v205
	v_add_u32_e32 v205, 0x17de8, v205
	ds_read2_b32 v[230:231], v221 offset1:1
	s_waitcnt lgkmcnt(14)
	v_pk_add_f32 v[96:97], v[96:97], v[176:177]
	ds_read2_b32 v[176:177], v205 offset1:1
	s_waitcnt lgkmcnt(3)
	v_pk_add_f32 v[108:109], v[108:109], v[226:227]
	v_pk_add_f32 v[106:107], v[106:107], v[212:213]
	s_waitcnt lgkmcnt(1)
	v_pk_add_f32 v[110:111], v[110:111], v[230:231]
	v_pk_add_f32 v[104:105], v[104:105], v[206:207]
	v_pk_add_f32 v[102:103], v[102:103], v[188:189]
	v_pk_add_f32 v[100:101], v[100:101], v[184:185]
	v_pk_add_f32 v[98:99], v[98:99], v[180:181]
	s_waitcnt lgkmcnt(0)
	v_pk_add_f32 v[94:95], v[94:95], v[176:177]
	v_pk_add_f32 v[92:93], v[92:93], v[228:229]
	v_pk_add_f32 v[90:91], v[90:91], v[224:225]
	v_pk_add_f32 v[88:89], v[88:89], v[210:211]
	v_pk_add_f32 v[86:87], v[86:87], v[190:191]
	v_pk_add_f32 v[84:85], v[84:85], v[186:187]
	v_pk_add_f32 v[82:83], v[82:83], v[182:183]
	v_pk_add_f32 v[80:81], v[80:81], v[178:179]
	s_nop 0
	s_branch .LBB0_241

.Latt_a_stg:
.Latt_a_bar:
	s_add_i32 s4, s65, 1
	s_cmp_lt_u32 s4, s66
	s_cbranch_scc0 .Lw0_a
	s_cmp_gt_u32 s56, 4
	s_cbranch_scc1 .Lw4_a
	s_waitcnt vmcnt(5) lgkmcnt(0)
	s_branch .Lwd_a

.Lwd_a:
	s_barrier
	s_add_i32 s4, s65, 1
	s_cmp_ge_u32 s4, s66
	s_cbranch_scc1 .Latt_a_nod
	s_add_i32 s4, s65, 2
	s_cmp_ge_u32 s4, s66
	s_cbranch_scc1 .Latt_a_nok
	s_add_i32 m0, s5, s32
	s_nop 0
	global_load_lds_dwordx4 v[128:129], off
	s_add_i32 m0, m0, 0x2000
	v_lshl_add_u64 v[128:129], v[128:129], 0, s[78:79]
	global_load_lds_dwordx4 v[130:131], off
	v_lshl_add_u64 v[130:131], v[130:131], 0, s[78:79]
	s_cmp_eq_u32 s56, 0
	s_cbranch_scc0 .Ldk_a
	s_add_i32 m0, s5, 0x4000
	s_nop 0
	global_load_lds_dwordx4 v[136:137], off
	v_lshl_add_u64 v[136:137], v[136:137], 0, s[78:79]
.Ldk_a:
.Latt_a_nok:
	s_mul_i32 s29, s87, 0x5000
	s_add_i32 s29, s29, 0x8800
	s_add_i32 m0, s29, s32
	s_nop 0
	global_load_lds_dwordx4 v[132:133], off
	s_add_i32 m0, m0, 0x2000
	v_lshl_add_u64 v[132:133], v[132:133], 0, s[78:79]
	global_load_lds_dwordx4 v[134:135], off
	v_lshl_add_u64 v[134:135], v[134:135], 0, s[78:79]
	s_cmp_eq_u32 s56, 0
	s_cbranch_scc1 .Ldv_a
	s_cmp_gt_u32 s56, 4
	s_cbranch_scc1 .Ldv_a
	s_add_i32 m0, s29, s32
	s_add_i32 m0, m0, 0x3c00
	s_nop 0
	global_load_lds_dwordx4 v[136:137], off
	v_lshl_add_u64 v[136:137], v[136:137], 0, s[78:79]
.Ldv_a:
.Latt_a_nod:
	s_nop 9
	v_max_f32_e32 v176, v80, v80
	v_max_f32_e32 v177, v96, v96
	v_max_f32_e32 v176, v177, v176
	v_max3_f32 v177, v81, v98, v82
	v_max3_f32 v176, v176, v97, v99
	v_max3_f32 v177, v177, v100, v84
	v_max3_f32 v176, v176, v83, v101
	v_max3_f32 v177, v177, v102, v86
	v_max3_f32 v176, v176, v85, v103
	v_max3_f32 v177, v177, v104, v88
	v_max3_f32 v176, v176, v87, v105
	v_max3_f32 v177, v177, v106, v90
	v_max3_f32 v176, v176, v89, v107
	v_max3_f32 v177, v177, v108, v92
	v_max3_f32 v176, v176, v91, v109
	v_max3_f32 v177, v177, v110, v94
	v_max3_f32 v176, v176, v93, v111
	v_max3_f32 v176, v176, v95, v177
	v_mov_b32_e32 v177, v176
	s_nop 1
	v_permlane32_swap_b32_e32 v176, v177
	v_max_f32_e32 v177, v177, v177
	v_max_f32_e32 v176, v176, v176
	v_max_f32_e32 v176, v176, v177
	s_mov_b32 s4, 0x41000000
	v_cmp_lt_f32_e32 vcc, s4, v176
	s_cbranch_vccz .Latt_a_exp
	v_max_f32_e32 v64, v176, v176
	v_max_f32_e32 v66, 0, v64
	v_exp_f32_e64 v176, -v66
	v_add_f32_e32 v173, v173, v66
	v_xor_b32_e32 v64, 0x80000000, v173
	v_pk_add_f32 v[96:97], v[96:97], v[66:67] op_sel_hi:[1,0] neg_lo:[0,1] neg_hi:[0,1]
	v_pk_add_f32 v[80:81], v[80:81], v[66:67] op_sel_hi:[1,0] neg_lo:[0,1] neg_hi:[0,1]
	v_pk_add_f32 v[98:99], v[98:99], v[66:67] op_sel_hi:[1,0] neg_lo:[0,1] neg_hi:[0,1]
	v_pk_add_f32 v[82:83], v[82:83], v[66:67] op_sel_hi:[1,0] neg_lo:[0,1] neg_hi:[0,1]
	v_pk_add_f32 v[100:101], v[100:101], v[66:67] op_sel_hi:[1,0] neg_lo:[0,1] neg_hi:[0,1]
	v_pk_add_f32 v[84:85], v[84:85], v[66:67] op_sel_hi:[1,0] neg_lo:[0,1] neg_hi:[0,1]
	v_pk_add_f32 v[102:103], v[102:103], v[66:67] op_sel_hi:[1,0] neg_lo:[0,1] neg_hi:[0,1]
	v_pk_add_f32 v[86:87], v[86:87], v[66:67] op_sel_hi:[1,0] neg_lo:[0,1] neg_hi:[0,1]
	v_pk_add_f32 v[104:105], v[104:105], v[66:67] op_sel_hi:[1,0] neg_lo:[0,1] neg_hi:[0,1]
	v_pk_add_f32 v[88:89], v[88:89], v[66:67] op_sel_hi:[1,0] neg_lo:[0,1] neg_hi:[0,1]
	v_pk_add_f32 v[106:107], v[106:107], v[66:67] op_sel_hi:[1,0] neg_lo:[0,1] neg_hi:[0,1]
	v_pk_add_f32 v[90:91], v[90:91], v[66:67] op_sel_hi:[1,0] neg_lo:[0,1] neg_hi:[0,1]
	v_pk_add_f32 v[108:109], v[108:109], v[66:67] op_sel_hi:[1,0] neg_lo:[0,1] neg_hi:[0,1]
	v_pk_add_f32 v[92:93], v[92:93], v[66:67] op_sel_hi:[1,0] neg_lo:[0,1] neg_hi:[0,1]
	v_pk_add_f32 v[110:111], v[110:111], v[66:67] op_sel_hi:[1,0] neg_lo:[0,1] neg_hi:[0,1]
	v_pk_add_f32 v[94:95], v[94:95], v[66:67] op_sel_hi:[1,0] neg_lo:[0,1] neg_hi:[0,1]
	v_mov_b32_e32 v65, v64
	v_mov_b32_e32 v66, v64
	v_mov_b32_e32 v67, v64
	v_mov_b32_e32 v68, v64
	v_mov_b32_e32 v69, v64
	v_mov_b32_e32 v70, v64
	v_mov_b32_e32 v71, v64
	v_mov_b32_e32 v72, v64
	v_mov_b32_e32 v73, v64
	v_mov_b32_e32 v74, v64
	v_mov_b32_e32 v75, v64
	v_mov_b32_e32 v76, v64
	v_mov_b32_e32 v77, v64
	v_mov_b32_e32 v78, v64
	v_mov_b32_e32 v79, v64
	v_pk_mul_f32 v[46:47], v[46:47], v[176:177] op_sel_hi:[1,0]
	v_pk_mul_f32 v[44:45], v[44:45], v[176:177] op_sel_hi:[1,0]
	v_pk_mul_f32 v[42:43], v[42:43], v[176:177] op_sel_hi:[1,0]
	v_pk_mul_f32 v[40:41], v[40:41], v[176:177] op_sel_hi:[1,0]
	v_pk_mul_f32 v[38:39], v[38:39], v[176:177] op_sel_hi:[1,0]
	v_pk_mul_f32 v[36:37], v[36:37], v[176:177] op_sel_hi:[1,0]
	v_pk_mul_f32 v[34:35], v[34:35], v[176:177] op_sel_hi:[1,0]
	v_pk_mul_f32 v[32:33], v[32:33], v[176:177] op_sel_hi:[1,0]
	v_pk_mul_f32 v[30:31], v[30:31], v[176:177] op_sel_hi:[1,0]
	v_pk_mul_f32 v[28:29], v[28:29], v[176:177] op_sel_hi:[1,0]
	v_pk_mul_f32 v[26:27], v[26:27], v[176:177] op_sel_hi:[1,0]
	v_pk_mul_f32 v[24:25], v[24:25], v[176:177] op_sel_hi:[1,0]
	v_pk_mul_f32 v[22:23], v[22:23], v[176:177] op_sel_hi:[1,0]
	v_pk_mul_f32 v[20:21], v[20:21], v[176:177] op_sel_hi:[1,0]
	v_pk_mul_f32 v[18:19], v[18:19], v[176:177] op_sel_hi:[1,0]
	v_pk_mul_f32 v[16:17], v[16:17], v[176:177] op_sel_hi:[1,0]
	v_pk_mul_f32 v[14:15], v[14:15], v[176:177] op_sel_hi:[1,0]
	v_pk_mul_f32 v[12:13], v[12:13], v[176:177] op_sel_hi:[1,0]
	v_pk_mul_f32 v[10:11], v[10:11], v[176:177] op_sel_hi:[1,0]
	v_pk_mul_f32 v[8:9], v[8:9], v[176:177] op_sel_hi:[1,0]
	v_pk_mul_f32 v[6:7], v[6:7], v[176:177] op_sel_hi:[1,0]
	v_pk_mul_f32 v[4:5], v[4:5], v[176:177] op_sel_hi:[1,0]
	v_pk_mul_f32 v[2:3], v[2:3], v[176:177] op_sel_hi:[1,0]
	v_pk_mul_f32 v[0:1], v[0:1], v[176:177] op_sel_hi:[1,0]
	v_pk_mul_f32 v[62:63], v[62:63], v[176:177] op_sel_hi:[1,0]
	v_pk_mul_f32 v[60:61], v[60:61], v[176:177] op_sel_hi:[1,0]
	v_pk_mul_f32 v[58:59], v[58:59], v[176:177] op_sel_hi:[1,0]
	v_pk_mul_f32 v[56:57], v[56:57], v[176:177] op_sel_hi:[1,0]
	v_pk_mul_f32 v[54:55], v[54:55], v[176:177] op_sel_hi:[1,0]
	v_pk_mul_f32 v[52:53], v[52:53], v[176:177] op_sel_hi:[1,0]
	v_pk_mul_f32 v[50:51], v[50:51], v[176:177] op_sel_hi:[1,0]
	v_pk_mul_f32 v[48:49], v[48:49], v[176:177] op_sel_hi:[1,0]
	v_mul_f32_e32 v172, v172, v176
